# v048 with attention stagger s_sleep 24 instead of 12
# baseline (speedup 1.0000x reference)
; #define ATT_ISSUE2(p_, st_) do { LAS unsigned char* sp_ = lds + (st_) * STG2; const int ta_ = dual ? (p_) : 2 * (p_), tb_ = dual ? (p_) : 2 * (p_) + 1; ATT_ISSUE1(u, ta_, sp_); ATT_ISSUEM(ta_, sp_ + 2 * STAGEB); \
;         if (dual || tb_ < u.ntiles) { ATT_ISSUE1(ub, tb_, sp_ + STAGEB); ATT_ISSUEM(tb_, sp_ + 2 * STAGEB + MSKB); } } while (0)
;     ...
;         for (int p = p0; p < npairs; ++p) {
;             asm volatile("s_waitcnt vmcnt(0)" ::: "memory");
;             __builtin_amdgcn_s_barrier(); asm volatile("" ::: "memory");
;             if (p + 1 < npairs) ATT_ISSUE2(p + 1, (p + 1) & 1);
.LBB0_579:
	s_add_i32 s27, s2, 1
	s_waitcnt vmcnt(0)
	s_barrier
	v_readlane_b32 s98, v254, 11
	s_nop 3
	s_cmp_lt_u32 s98, 4
	s_cbranch_scc1 .Lstag_579
	s_sleep 24

; #define ATT_ISSUE2(p_, st_) do { LAS unsigned char* sp_ = lds + (st_) * STG2; const int ta_ = dual ? (p_) : 2 * (p_), tb_ = dual ? (p_) : 2 * (p_) + 1; ATT_ISSUE1(u, ta_, sp_); ATT_ISSUEM(ta_, sp_ + 2 * STAGEB); \
;         if (dual || tb_ < u.ntiles) { ATT_ISSUE1(ub, tb_, sp_ + STAGEB); ATT_ISSUEM(tb_, sp_ + 2 * STAGEB + MSKB); } } while (0)
;     ...
;         for (int p = p0; p < npairs; ++p) {
;             asm volatile("s_waitcnt vmcnt(0)" ::: "memory");
;             __builtin_amdgcn_s_barrier(); asm volatile("" ::: "memory");
;             if (p + 1 < npairs) ATT_ISSUE2(p + 1, (p + 1) & 1);
.LBB0_2104:
	s_waitcnt vmcnt(0)
	s_barrier
	v_readlane_b32 s98, v254, 11
	s_nop 3
	s_cmp_lt_u32 s98, 4
	s_cbranch_scc1 .Lstag_2104
	s_sleep 24

; #define ATT_ISSUE2(p_, st_) do { LAS unsigned char* sp_ = lds + (st_) * STG2; const int ta_ = dual ? (p_) : 2 * (p_), tb_ = dual ? (p_) : 2 * (p_) + 1; ATT_ISSUE1(u, ta_, sp_); ATT_ISSUEM(ta_, sp_ + 2 * STAGEB); \
;         if (dual || tb_ < u.ntiles) { ATT_ISSUE1(ub, tb_, sp_ + STAGEB); ATT_ISSUEM(tb_, sp_ + 2 * STAGEB + MSKB); } } while (0)
;     ...
;         for (int p = p0; p < npairs; ++p) {
;             asm volatile("s_waitcnt vmcnt(0)" ::: "memory");
;             __builtin_amdgcn_s_barrier(); asm volatile("" ::: "memory");
;             if (p + 1 < npairs) ATT_ISSUE2(p + 1, (p + 1) & 1);
.LBB0_3301:
	s_add_i32 s96, s97, 1
	s_waitcnt vmcnt(0)
	s_barrier
	v_readlane_b32 s98, v254, 11
	s_nop 3
	s_cmp_lt_u32 s98, 4
	s_cbranch_scc1 .Lstag_3301
	s_sleep 24
